# k34 + attention: next-item prefetch block (address math + 10 global loads) moved behind the score MFMAs so it overlaps the matrix pipe (MFMA<->VALU interleave)
# baseline (speedup 1.0000x reference)
; __device__ void phase_attn(const Params& p, unsigned char* smem, int wave) {
;     ...
;     if ((int)blockIdx.x < npairs) { ATT_DECODE(blockIdx.x) ATT_LOAD(); }
;     for (int pr = blockIdx.x; pr < npairs; pr += gridDim.x) {
;         ATT_DECODE(pr)
;         bf16_t* ato = (bf16_t*)(p.ws + (br < 2 ? WS_RA + br * ATO_STRIDE_01 : WS_ATO2));
;         __syncthreads();
;         const int hs = fresh_tid(wave);
; #pragma unroll
;         for (int c_ = 0; c_ < 2; ++c_) { const int e = hs + 512 * c_; *(u32x4*)(Qs + (e >> 3) * ATT_LD + (e & 7) * 8) = qr[c_]; }
; #pragma unroll
;         for (int c_ = 0; c_ < 4; ++c_) { const int e = hs + 512 * c_; *(u32x4*)(Ks + (e >> 3) * ATT_LD + (e & 7) * 8) = kr[c_]; *(u32x4*)(Vs + (e >> 3) * ATT_LD + (e & 7) * 8) = vr[c_]; }
;         __syncthreads();
;         if (pr + (int)gridDim.x < npairs) { ATT_DECODE(pr + gridDim.x) ATT_LOAD(); }
;         const bf16x8 qf0 = *(const bf16x8*)(Qs + (16 * w4 + ql) * ATT_LD + gq * 8), qf1 = *(const bf16x8*)(Qs + (16 * w4 + ql) * ATT_LD + 32 + gq * 8);
;         f32x4 sc[10];
; #pragma unroll
;         for (int kt = 0; kt < 9; ++kt) { const bf16_t* kr = Ks + (16 * w4 + 16 * kt + ql) * ATT_LD + gq * 8;
;             f32x4 a = (f32x4){0.f, 0.f, 0.f, 0.f};
;             a = __builtin_amdgcn_mfma_f32_16x16x32_bf16(*(const bf16x8*)kr, qf0, a, 0, 0, 0);
;             a = __builtin_amdgcn_mfma_f32_16x16x32_bf16(*(const bf16x8*)(kr + 32), qf1, a, 0, 0, 0);
;             sc[kt] = a; if (kt % 3 == 2) __builtin_amdgcn_sched_barrier(0); }
.LBB0_722:
	s_waitcnt lgkmcnt(0)
	s_barrier
	v_mbcnt_lo_u32_b32 v12, -1, 0
	v_mbcnt_hi_u32_b32 v12, -1, v12
	s_add_i32 s56, s23, s93
	v_or_b32_e32 v13, s70, v12
	v_lshlrev_b32_e32 v12, 4, v12
	v_and_b32_e32 v12, 0x70, v12
	v_add_u32_e32 v12, 0, v12
	v_lshrrev_b32_e32 v14, 3, v13
	v_mad_u64_u32 v[46:47], s[18:19], v14, s33, v[12:13]
	v_add_u32_e32 v14, 0x200, v13
	v_lshrrev_b32_e32 v14, 3, v14
	v_mad_u64_u32 v[48:49], s[18:19], v14, s33, v[12:13]
	v_add_u32_e32 v14, 0x400, v13
	v_lshrrev_b32_e32 v14, 3, v14
	s_waitcnt vmcnt(18)
	ds_write_b128 v46, v[0:3]
	s_waitcnt vmcnt(17)
	ds_write_b128 v48, v[4:7]
	ds_write_b128 v46, v[16:19] offset:18432
	ds_write_b128 v46, v[20:23] offset:55296
	ds_write_b128 v48, v[8:11] offset:18432
	ds_write_b128 v48, v[24:27] offset:55296
	v_mad_u64_u32 v[46:47], s[18:19], v14, s33, v[12:13]
	v_add_u32_e32 v13, 0x600, v13
	s_cmpk_gt_i32 s56, 0x3bff
	v_lshrrev_b32_e32 v13, 3, v13
	s_cselect_b64 s[46:47], -1, 0
	v_mad_u64_u32 v[12:13], s[18:19], v13, s33, v[12:13]
	s_and_b64 vcc, exec, s[46:47]
	ds_write_b128 v46, v[28:31] offset:18432
	ds_write_b128 v46, v[32:35] offset:55296
	ds_write_b128 v12, v[36:39] offset:18432
	ds_write_b128 v12, v[40:43] offset:55296
	s_waitcnt lgkmcnt(0)
	s_barrier
	ds_read_b128 v[232:235], v140 offset:18432
	ds_read_b128 v[186:189], v140
	ds_read_b128 v[50:53], v140 offset:18496
	ds_read_b128 v[190:193], v140 offset:64
	ds_read_b128 v[54:57], v140 offset:20736
	ds_read_b128 v[58:61], v140 offset:20800
	ds_read_b128 v[236:239], v140 offset:23040
	ds_read_b128 v[240:243], v140 offset:23104
	ds_read_b128 v[244:247], v140 offset:25344
	ds_read_b128 v[248:251], v140 offset:25408
	v_readlane_b32 s28, v253, 8
	v_readlane_b32 s30, v253, 10
	v_readlane_b32 s31, v253, 11
	s_add_u32 s59, s30, s20
	s_mul_i32 s18, s22, 0xfffffd80
	s_waitcnt lgkmcnt(8)
	v_mfma_f32_16x16x32_bf16 v[46:49], v[232:235], v[186:189], 0
	s_mul_i32 s19, s22, 0xfffec000
	s_addc_u32 s60, s31, s21
	s_add_i32 s18, s23, s18
	s_waitcnt lgkmcnt(6)
	v_mfma_f32_16x16x32_bf16 v[194:197], v[50:53], v[190:193], v[46:49]
	s_add_i32 s19, s48, s19
	s_and_b32 s57, s22, 7
	s_and_b32 s19, s19, 0xfffff800
	s_waitcnt lgkmcnt(5)
	v_mfma_f32_16x16x32_bf16 v[50:53], v[54:57], v[186:189], 0
	s_and_b32 s20, s18, 15
	s_add_i32 s21, s18, 0xfffffe00
	s_cmpk_lt_i32 s18, 0x200
	s_cselect_b32 s18, s20, s21
	s_cselect_b32 s20, s50, 0x4000
	s_cselect_b32 s61, s19, 0x10000
	s_cmp_eq_u32 s42, 1
	s_cselect_b32 s19, 4, 16
	s_cselect_b32 s21, 2, 4
	s_cmp_lt_u32 s22, 8
	s_waitcnt lgkmcnt(3)
	v_mfma_f32_16x16x32_bf16 v[46:49], v[236:239], v[186:189], 0
	s_cselect_b32 s22, 1, s19
	s_cselect_b32 s58, 0, s21
	s_add_i32 s19, s22, -1
	s_lshr_b32 s63, s20, s58
	s_and_b32 s62, s19, s18
	s_lshr_b32 s20, s18, s58
	v_readlane_b32 s29, v253, 9
	v_mfma_f32_16x16x32_bf16 v[198:201], v[58:61], v[190:193], v[50:53]
	s_waitcnt lgkmcnt(2)
	v_mfma_f32_16x16x32_bf16 v[202:205], v[240:243], v[190:193], v[46:49]
	s_nop 2
	ds_read_b128 v[54:57], v140 offset:27648
	ds_read_b128 v[58:61], v140 offset:27712
	s_waitcnt lgkmcnt(3)
	v_mfma_f32_16x16x32_bf16 v[46:49], v[244:247], v[186:189], 0
	s_waitcnt lgkmcnt(2)
	v_mfma_f32_16x16x32_bf16 v[206:209], v[248:251], v[190:193], v[46:49]
	ds_read_b128 v[50:53], v140 offset:30016
	s_nop 4
	ds_read_b128 v[46:49], v140 offset:29952
	s_waitcnt lgkmcnt(3)
	v_mfma_f32_16x16x32_bf16 v[54:57], v[54:57], v[186:189], 0
	s_waitcnt lgkmcnt(0)
	v_mfma_f32_16x16x32_bf16 v[46:49], v[46:49], v[186:189], 0
	v_mfma_f32_16x16x32_bf16 v[62:65], v[58:61], v[190:193], v[54:57]
	v_mfma_f32_16x16x32_bf16 v[58:61], v[50:53], v[190:193], v[46:49]
	s_nop 5
	ds_read_b128 v[46:49], v140 offset:32256
	ds_read_b128 v[50:53], v140 offset:32320
	ds_read_b128 v[54:57], v140 offset:34560
	ds_read_b128 v[210:213], v140 offset:34624
	s_waitcnt lgkmcnt(3)
	v_mfma_f32_16x16x32_bf16 v[46:49], v[46:49], v[186:189], 0
	s_waitcnt lgkmcnt(1)
	v_mfma_f32_16x16x32_bf16 v[214:217], v[54:57], v[186:189], 0
	v_mfma_f32_16x16x32_bf16 v[54:57], v[50:53], v[190:193], v[46:49]
	s_nop 4
	ds_read_b128 v[46:49], v140 offset:36864
	s_waitcnt lgkmcnt(1)
	v_mfma_f32_16x16x32_bf16 v[50:53], v[210:213], v[190:193], v[214:217]
	ds_read_b128 v[210:213], v140 offset:36928
	s_waitcnt lgkmcnt(1)
	v_mfma_f32_16x16x32_bf16 v[46:49], v[46:49], v[186:189], 0
	s_waitcnt lgkmcnt(0)
	v_mfma_f32_16x16x32_bf16 v[46:49], v[210:213], v[190:193], v[46:49]
	s_cbranch_vccnz .LBB0_732
	s_mul_hi_i32 s18, s56, 0x66666667
	s_lshr_b32 s19, s18, 31
	s_ashr_i32 s18, s18, 8
	s_add_i32 s18, s18, s19
	s_mul_i32 s19, s18, 0xfffffd80
	s_mul_i32 s27, s18, 0xfffec000
	s_add_i32 s28, s49, s48
	s_add_i32 s19, s56, s19
	s_add_i32 s28, s28, s27
	s_and_b32 s26, s18, -8
	s_and_b32 s27, s28, 0xfffff800
	s_and_b32 s28, s19, 15
	s_add_i32 s29, s19, 0xfffffe00
	s_cmp_eq_u32 s26, 8
	s_cselect_b32 s26, 2, 4
	s_cselect_b32 s30, 3, 15
	s_cmp_lt_u32 s18, 8
	s_cselect_b32 s26, 0, s26
	s_cselect_b32 s30, 0, s30
	s_cmpk_lt_i32 s19, 0x200
	s_cselect_b32 s19, s28, s29
	s_cselect_b32 s27, s27, 0x10000
	s_cselect_b32 s28, s50, 0x4000
	s_and_b32 s29, s30, s19
	s_lshr_b32 s19, s19, s26
	v_mbcnt_lo_u32_b32 v0, -1, 0
	v_mbcnt_hi_u32_b32 v0, -1, v0
	s_lshl_b32 s18, s18, 6
	v_or_b32_e32 v13, s70, v0
	s_lshl_b32 s19, s19, 7
	s_and_b32 s18, s18, 0x1c0
	v_lshlrev_b32_e32 v0, 3, v0
	v_ashrrev_i32_e32 v8, 3, v13
	v_add_u32_e32 v2, 0x200, v13
	v_and_or_b32 v12, v0, 56, s18
	v_add_u32_e32 v0, s19, v8
	v_ashrrev_i32_e32 v24, 3, v2
	s_or_b32 s27, s29, s27
	v_lshlrev_b32_e32 v0, s26, v0
	v_add_u32_e32 v2, s19, v24
	v_add_u32_e32 v0, s27, v0
	v_lshlrev_b32_e32 v2, s26, v2
	v_mul_lo_u32 v0, v0, s3
	v_add_u32_e32 v2, s27, v2
	v_or_b32_e32 v14, v0, v12
	v_mul_lo_u32 v2, v2, s3
	v_lshl_add_u64 v[0:1], v[14:15], 1, s[38:39]
	v_or_b32_e32 v14, v2, v12
	v_lshl_add_u64 v[4:5], v[14:15], 1, s[38:39]
	global_load_dwordx4 v[0:3], v[0:1], off
	s_nop 0
	global_load_dwordx4 v[4:7], v[4:5], off
	s_sub_i32 s29, s19, 64
	s_lshr_b32 s28, s28, s26
	v_add_u32_e32 v14, s29, v8
	v_mov_b32_e32 v10, v44
	v_mov_b32_e32 v11, v44
	v_cmp_lt_i32_e32 vcc, -1, v14
	v_cmp_gt_i32_e64 s[18:19], s28, v14
	v_mov_b32_e32 v8, 0
	v_mov_b32_e32 v9, v44
	v_mov_b64_e32 v[18:19], v[10:11]
	v_mov_b64_e32 v[22:23], v[10:11]
	s_and_b64 s[30:31], vcc, s[18:19]
	v_mov_b64_e32 v[16:17], v[8:9]
	v_mov_b64_e32 v[20:21], v[8:9]
	s_and_saveexec_b64 s[18:19], s[30:31]
	s_cbranch_execz .LBB0_725
	v_lshlrev_b32_e32 v14, s26, v14
	v_add_u32_e32 v14, s27, v14
	v_mul_lo_u32 v14, v14, s3
	v_or_b32_e32 v14, v14, v12
	v_lshl_add_u64 v[20:21], v[14:15], 1, s[38:39]
	global_load_dwordx4 v[16:19], v[20:21], off offset:1024
	s_nop 0
	global_load_dwordx4 v[20:23], v[20:21], off offset:2048

.LBB0_727:
	s_or_b64 exec, exec, s[18:19]
	v_add_u32_e32 v14, 0x400, v13
	v_ashrrev_i32_e32 v14, 3, v14
	v_add_u32_e32 v14, s29, v14
	v_mov_b32_e32 v45, v44
	v_cmp_lt_i32_e32 vcc, -1, v14
	v_cmp_gt_i32_e64 s[18:19], s28, v14
	v_mov_b32_e32 v232, v44
	v_mov_b32_e32 v233, v44
	v_mov_b64_e32 v[28:29], v[44:45]
	v_mov_b64_e32 v[32:33], v[44:45]
	s_and_b64 s[30:31], vcc, s[18:19]
	v_mov_b64_e32 v[30:31], v[232:233]
	v_mov_b64_e32 v[34:35], v[232:233]
	s_and_saveexec_b64 s[18:19], s[30:31]
	s_cbranch_execz .LBB0_729
	v_lshlrev_b32_e32 v14, s26, v14
	v_add_u32_e32 v14, s27, v14
	v_mul_lo_u32 v14, v14, s3
	v_or_b32_e32 v14, v14, v12
	v_lshl_add_u64 v[32:33], v[14:15], 1, s[38:39]
	global_load_dwordx4 v[28:31], v[32:33], off offset:1024
	s_nop 0
	global_load_dwordx4 v[32:35], v[32:33], off offset:2048

; __device__ void phase_attn(const Params& p, unsigned char* smem, int wave) {
;     ...
;         const float slope = exp2f(-(float)(h + 1)) * (float)d * 1.4426950408889634f;
;         const int qi = i0 + 16 * w4 + ql;
;         float mx = -1e30f;
; #pragma unroll
;         for (int kt = 0; kt < 9; ++kt)
; #pragma unroll
;             for (int j = 0; j < 4; ++j) { const int rel = 16 * kt + 4 * gq + j - 64 - ql; const int jk = qi + rel;
;                 const bool relok = (kt == 0) ? (rel >= -64) : ((kt == 8) ? (rel <= 64) : true);
;                 const bool ok = relok && ((unsigned)jk < (unsigned)Ls);
;                 const float v = ok ? sc[kt][j] * 0.18033688011112042f - slope * fabsf((float)rel) : -1e30f;
;                 sc[kt][j] = v; mx = fmaxf(mx, v); }
.LBB0_732:
	s_add_i32 s18, s57, 1
	v_cvt_f32_ubyte0_e32 v12, s18
	v_cmp_lt_f32_e32 vcc, s51, v12
	s_and_b64 s[18:19], vcc, exec
	s_cselect_b32 s18, 0xffffffc0, 0
	v_cndmask_b32_e32 v13, 0, v181, vcc
	v_sub_f32_e32 v12, v13, v12
	v_exp_f32_e32 v12, v12
	v_lshl_add_u32 v139, s20, 7, v67
	v_cvt_f32_ubyte0_e32 v13, s22
	v_or_b32_e32 v45, v139, v66
	v_ldexp_f32 v12, v12, s18
	v_mul_f32_e32 v13, v12, v13
	v_add_u32_e32 v12, v45, v143
	v_cmp_gt_u32_e64 s[26:27], s63, v12
	v_add_u32_e32 v12, v45, v144
	v_cmp_gt_u32_e64 s[28:29], s63, v12
	v_add_u32_e32 v12, v45, v145
	v_cmp_gt_u32_e64 s[30:31], s63, v12
	v_add_u32_e32 v12, v45, v146
	v_cmp_gt_u32_e64 s[34:35], s63, v12
	v_add_u32_e32 v12, v45, v174
	v_cmp_gt_u32_e64 s[22:23], s63, v12
	v_add_u32_e32 v12, v45, v175
	v_cmp_gt_u32_e64 s[20:21], s63, v12
	v_add_u32_e32 v12, v45, v176
	v_cmp_gt_u32_e32 vcc, s63, v12
	v_add_u32_e32 v12, v45, v177
	v_cmp_gt_u32_e64 s[18:19], s63, v12
	v_mov_b32_e32 v12, v49
	v_pk_mul_f32 v[12:13], v[12:13], s[44:45]
	v_mov_b32_e32 v186, v194
	v_mov_b32_e32 v187, v13
	v_pk_mul_f32 v[186:187], v[68:69], v[186:187]
	s_and_b64 s[26:27], s[24:25], s[26:27]
	v_sub_f32_e32 v49, v186, v187
	v_mov_b32_e32 v186, v195
	v_mov_b32_e32 v187, v13
	v_pk_mul_f32 v[186:187], v[70:71], v[186:187]
	v_cndmask_b32_e64 v194, v182, v49, s[26:27]
	v_sub_f32_e32 v49, v186, v187
	v_mov_b32_e32 v186, v196
	v_mov_b32_e32 v187, v13
	s_and_b64 s[26:27], s[4:5], s[28:29]
	v_pk_mul_f32 v[186:187], v[72:73], v[186:187]
	v_cndmask_b32_e64 v195, v182, v49, s[26:27]
	v_sub_f32_e32 v186, v186, v187
	s_and_b64 s[26:27], s[6:7], s[30:31]
	v_cndmask_b32_e64 v196, v182, v186, s[26:27]
	v_mov_b32_e32 v186, v197
	v_mov_b32_e32 v187, v13
	v_pk_mul_f32 v[186:187], v[74:75], v[186:187]
	s_and_b64 s[26:27], s[8:9], s[34:35]
	v_sub_f32_e32 v186, v186, v187
	v_cndmask_b32_e64 v197, v182, v186, s[26:27]
	v_mov_b32_e32 v186, v198
	v_mov_b32_e32 v187, v13
	v_add_u32_e32 v14, v45, v147
	v_pk_mul_f32 v[186:187], v[76:77], v[186:187]
	v_cmp_gt_u32_e64 s[26:27], s63, v14
	v_sub_f32_e32 v186, v186, v187
	v_mov_b32_e32 v187, v13
	v_cndmask_b32_e64 v14, v182, v186, s[26:27]
	v_mov_b32_e32 v186, v199
	v_add_u32_e32 v188, v45, v148
	v_pk_mul_f32 v[186:187], v[78:79], v[186:187]
	v_cmp_gt_u32_e64 s[26:27], s63, v188
	v_sub_f32_e32 v186, v186, v187
	v_mov_b32_e32 v187, v13
	v_cndmask_b32_e64 v188, v182, v186, s[26:27]
	v_mov_b32_e32 v186, v200
	v_add_u32_e32 v189, v45, v149
	v_pk_mul_f32 v[186:187], v[80:81], v[186:187]
	v_cmp_gt_u32_e64 s[26:27], s63, v189
	v_sub_f32_e32 v186, v186, v187
	v_mov_b32_e32 v187, v13
	v_cndmask_b32_e64 v189, v182, v186, s[26:27]
	v_mov_b32_e32 v186, v201
	v_add_u32_e32 v190, v45, v150
	v_pk_mul_f32 v[186:187], v[82:83], v[186:187]
	v_cmp_gt_u32_e64 s[26:27], s63, v190
	v_sub_f32_e32 v186, v186, v187
	v_mov_b32_e32 v187, v13
	v_cndmask_b32_e64 v190, v182, v186, s[26:27]
	v_mov_b32_e32 v186, v202
	v_add_u32_e32 v191, v45, v151
	v_pk_mul_f32 v[186:187], v[84:85], v[186:187]
	v_cmp_gt_u32_e64 s[26:27], s63, v191
	v_sub_f32_e32 v186, v186, v187
	v_mov_b32_e32 v187, v13
	v_cndmask_b32_e64 v191, v182, v186, s[26:27]
	v_mov_b32_e32 v186, v203
	v_add_u32_e32 v192, v45, v152
	v_pk_mul_f32 v[186:187], v[86:87], v[186:187]
	v_cmp_gt_u32_e64 s[26:27], s63, v192
	v_sub_f32_e32 v186, v186, v187
	v_mov_b32_e32 v187, v13
	v_cndmask_b32_e64 v192, v182, v186, s[26:27]
	v_mov_b32_e32 v186, v204
	v_add_u32_e32 v193, v45, v153
	v_pk_mul_f32 v[186:187], v[88:89], v[186:187]
	v_cmp_gt_u32_e64 s[26:27], s63, v193
	v_sub_f32_e32 v186, v186, v187
	v_mov_b32_e32 v187, v13
	v_cndmask_b32_e64 v193, v182, v186, s[26:27]
	v_mov_b32_e32 v186, v205
	v_add_u32_e32 v210, v45, v154
	v_pk_mul_f32 v[186:187], v[90:91], v[186:187]
	v_cmp_gt_u32_e64 s[26:27], s63, v210
	v_sub_f32_e32 v186, v186, v187
	v_mov_b32_e32 v187, v13
	v_cndmask_b32_e64 v198, v182, v186, s[26:27]
	v_mov_b32_e32 v186, v206
	v_add_u32_e32 v211, v45, v155
	v_pk_mul_f32 v[186:187], v[92:93], v[186:187]
	v_cmp_gt_u32_e64 s[26:27], s63, v211
	v_sub_f32_e32 v186, v186, v187
	v_mov_b32_e32 v187, v13
	v_cndmask_b32_e64 v199, v182, v186, s[26:27]
	v_mov_b32_e32 v186, v207
	v_add_u32_e32 v212, v45, v156
	v_pk_mul_f32 v[186:187], v[94:95], v[186:187]
	v_cmp_gt_u32_e64 s[26:27], s63, v212
	v_sub_f32_e32 v186, v186, v187
	v_mov_b32_e32 v187, v13
	v_cndmask_b32_e64 v200, v182, v186, s[26:27]
	v_mov_b32_e32 v186, v208
	v_add_u32_e32 v213, v45, v157
	v_pk_mul_f32 v[186:187], v[96:97], v[186:187]
	v_cmp_gt_u32_e64 s[26:27], s63, v213
	v_sub_f32_e32 v186, v186, v187
	v_mov_b32_e32 v187, v13
	v_cndmask_b32_e64 v201, v182, v186, s[26:27]
	v_mov_b32_e32 v186, v209
	v_add_u32_e32 v214, v45, v158
	v_pk_mul_f32 v[186:187], v[98:99], v[186:187]
	v_cmp_gt_u32_e64 s[26:27], s63, v214
	v_sub_f32_e32 v186, v186, v187
	v_mov_b32_e32 v187, v13
	v_cndmask_b32_e64 v202, v182, v186, s[26:27]
	v_mov_b32_e32 v186, v62
	v_add_u32_e32 v215, v45, v142
	v_pk_mul_f32 v[186:187], v[100:101], v[186:187]
	v_cmp_gt_u32_e64 s[26:27], s63, v215
	v_sub_f32_e32 v62, v186, v187
	v_add_u32_e32 v216, v45, v159
	v_cndmask_b32_e64 v186, v182, v62, s[26:27]
	v_mov_b32_e32 v62, v63
	v_mov_b32_e32 v63, v13
	v_pk_mul_f32 v[62:63], v[102:103], v[62:63]
	v_cmp_gt_u32_e64 s[26:27], s63, v216
	v_sub_f32_e32 v62, v62, v63
	v_mov_b32_e32 v63, v13
	v_cndmask_b32_e64 v187, v182, v62, s[26:27]
	v_mov_b32_e32 v62, v64
	v_add_u32_e32 v217, v45, v160
	v_pk_mul_f32 v[62:63], v[104:105], v[62:63]
	v_cmp_gt_u32_e64 s[26:27], s63, v217
	v_sub_f32_e32 v62, v62, v63
	v_mov_b32_e32 v63, v13
	v_cndmask_b32_e64 v64, v182, v62, s[26:27]
	v_mov_b32_e32 v62, v65
	v_add_u32_e32 v218, v45, v161
	v_pk_mul_f32 v[62:63], v[106:107], v[62:63]
; __device__ void phase_attn(const Params& p, unsigned char* smem, int wave) {
;     ...
; #pragma unroll
;         for (int kt = 0; kt < 9; ++kt)
; #pragma unroll
;             for (int j = 0; j < 4; ++j) { const int rel = 16 * kt + 4 * gq + j - 64 - ql; const int jk = qi + rel;
;                 const bool relok = (kt == 0) ? (rel >= -64) : ((kt == 8) ? (rel <= 64) : true);
;                 const bool ok = relok && ((unsigned)jk < (unsigned)Ls);
;                 const float v = ok ? sc[kt][j] * 0.18033688011112042f - slope * fabsf((float)rel) : -1e30f;
;                 sc[kt][j] = v; mx = fmaxf(mx, v); }
;         mx = fmaxf(mx, __shfl_xor(mx, 16)); mx = fmaxf(mx, __shfl_xor(mx, 32));
	v_cmp_gt_u32_e64 s[26:27], s63, v218
	v_sub_f32_e32 v62, v62, v63
	v_mov_b32_e32 v63, v13
	v_cndmask_b32_e64 v65, v182, v62, s[26:27]
	v_mov_b32_e32 v62, v58
	v_add_u32_e32 v219, v45, v162
	v_pk_mul_f32 v[62:63], v[62:63], v[108:109]
	v_cmp_gt_u32_e64 s[26:27], s63, v219
	v_sub_f32_e32 v58, v62, v63
	v_add_u32_e32 v220, v45, v163
	v_cndmask_b32_e64 v62, v182, v58, s[26:27]
	v_mov_b32_e32 v58, v59
	v_mov_b32_e32 v59, v13
	v_pk_mul_f32 v[58:59], v[58:59], v[110:111]
	v_cmp_gt_u32_e64 s[26:27], s63, v220
	v_sub_f32_e32 v58, v58, v59
	v_mov_b32_e32 v59, v13
	v_cndmask_b32_e64 v63, v182, v58, s[26:27]
	v_mov_b32_e32 v58, v60
	v_add_u32_e32 v221, v45, v164
	v_pk_mul_f32 v[58:59], v[58:59], v[112:113]
	v_cmp_gt_u32_e64 s[26:27], s63, v221
	v_sub_f32_e32 v58, v58, v59
	v_mov_b32_e32 v59, v13
	v_cndmask_b32_e64 v60, v182, v58, s[26:27]
	v_mov_b32_e32 v58, v61
	v_add_u32_e32 v222, v45, v165
	v_pk_mul_f32 v[58:59], v[58:59], v[114:115]
	v_cmp_gt_u32_e64 s[26:27], s63, v222
	v_sub_f32_e32 v58, v58, v59
	v_mov_b32_e32 v59, v13
	v_cndmask_b32_e64 v61, v182, v58, s[26:27]
	v_mov_b32_e32 v58, v54
	v_add_u32_e32 v223, v45, v166
	v_pk_mul_f32 v[58:59], v[58:59], v[116:117]
	v_cmp_gt_u32_e64 s[26:27], s63, v223
	v_sub_f32_e32 v54, v58, v59
	v_add_u32_e32 v224, v45, v167
	v_cndmask_b32_e64 v58, v182, v54, s[26:27]
	v_mov_b32_e32 v54, v55
	v_mov_b32_e32 v55, v13
	v_pk_mul_f32 v[54:55], v[54:55], v[118:119]
	v_cmp_gt_u32_e64 s[26:27], s63, v224
	v_sub_f32_e32 v54, v54, v55
	v_mov_b32_e32 v55, v13
	v_cndmask_b32_e64 v59, v182, v54, s[26:27]
	v_mov_b32_e32 v54, v56
	v_add_u32_e32 v225, v45, v168
	v_pk_mul_f32 v[54:55], v[54:55], v[120:121]
	v_cmp_gt_u32_e64 s[26:27], s63, v225
	v_sub_f32_e32 v54, v54, v55
	v_mov_b32_e32 v55, v13
	v_cndmask_b32_e64 v56, v182, v54, s[26:27]
	v_mov_b32_e32 v54, v57
	v_add_u32_e32 v226, v45, v169
	v_pk_mul_f32 v[54:55], v[54:55], v[122:123]
	v_cmp_gt_u32_e64 s[26:27], s63, v226
	v_sub_f32_e32 v54, v54, v55
	v_mov_b32_e32 v55, v13
	v_cndmask_b32_e64 v57, v182, v54, s[26:27]
	v_mov_b32_e32 v54, v50
	v_add_u32_e32 v227, v45, v170
	v_pk_mul_f32 v[54:55], v[54:55], v[124:125]
	v_cmp_gt_u32_e64 s[26:27], s63, v227
	v_sub_f32_e32 v50, v54, v55
	v_max3_f32 v49, v194, s52, v195
	v_cndmask_b32_e64 v54, v182, v50, s[26:27]
	v_mov_b32_e32 v50, v51
	v_mov_b32_e32 v51, v13
	v_add_u32_e32 v228, v45, v171
	v_max3_f32 v49, v49, v196, v197
	v_pk_mul_f32 v[50:51], v[50:51], v[126:127]
	v_max3_f32 v49, v49, v14, v188
	v_sub_f32_e32 v50, v50, v51
	v_cmp_gt_u32_e64 s[26:27], s63, v228
	v_max3_f32 v49, v49, v189, v190
	v_mov_b32_e32 v51, v13
	v_cndmask_b32_e64 v55, v182, v50, s[26:27]
	v_mov_b32_e32 v50, v52
	v_add_u32_e32 v229, v45, v172
	v_max3_f32 v49, v49, v191, v192
	v_pk_mul_f32 v[50:51], v[50:51], v[128:129]
	v_max3_f32 v49, v49, v193, v198
	v_sub_f32_e32 v50, v50, v51
	v_cmp_gt_u32_e64 s[26:27], s63, v229
	v_max3_f32 v49, v49, v199, v200
	v_mov_b32_e32 v51, v13
	v_cndmask_b32_e64 v52, v182, v50, s[26:27]
	v_mov_b32_e32 v50, v53
	v_add_u32_e32 v230, v45, v173
	v_max3_f32 v49, v49, v201, v202
	v_pk_mul_f32 v[50:51], v[50:51], v[130:131]
	v_max3_f32 v49, v49, v186, v187
	v_sub_f32_e32 v50, v50, v51
	v_cmp_gt_u32_e64 s[26:27], s63, v230
	v_max3_f32 v49, v49, v64, v65
	v_mov_b32_e32 v51, v13
	v_cndmask_b32_e64 v53, v182, v50, s[26:27]
	v_mov_b32_e32 v50, v46
	v_max3_f32 v49, v49, v62, v63
	v_pk_mul_f32 v[50:51], v[50:51], v[132:133]
	v_max3_f32 v49, v49, v60, v61
	v_sub_f32_e32 v46, v50, v51
	s_and_b64 s[22:23], s[10:11], s[22:23]
	v_max3_f32 v49, v49, v58, v59
	v_cndmask_b32_e64 v50, v182, v46, s[22:23]
	v_mov_b32_e32 v46, v47
	v_mov_b32_e32 v47, v13
	v_max3_f32 v49, v49, v56, v57
	v_pk_mul_f32 v[46:47], v[46:47], v[134:135]
	v_max3_f32 v49, v49, v54, v55
	v_sub_f32_e32 v46, v46, v47
	s_and_b64 s[20:21], s[12:13], s[20:21]
	v_max3_f32 v49, v49, v52, v53
	v_cndmask_b32_e64 v51, v182, v46, s[20:21]
	v_max3_f32 v203, v49, v50, v51
	v_mov_b32_e32 v49, v13
	v_pk_mul_f32 v[46:47], v[48:49], v[136:137]
	s_and_b64 vcc, s[14:15], vcc
	v_sub_f32_e32 v46, v46, v47
	v_and_b32_e32 v206, 64, v183
	v_cndmask_b32_e32 v47, v182, v46, vcc
	v_fma_f32 v12, -v13, v178, v12
	s_and_b64 vcc, s[16:17], s[18:19]
	v_xor_b32_e32 v46, 16, v183
	v_add_u32_e32 v48, 64, v206
	v_cndmask_b32_e32 v12, v182, v12, vcc
	v_cmp_lt_i32_e32 vcc, v46, v48
	v_max3_f32 v13, v203, v47, v12
	s_nop 0
	v_cndmask_b32_e32 v46, v183, v46, vcc
	v_lshlrev_b32_e32 v203, 2, v46
	ds_bpermute_b32 v46, v203, v13
	s_waitcnt lgkmcnt(0)
	v_max_f32_e32 v46, v46, v46
	v_max_f32_e32 v13, v13, v46
	v_xor_b32_e32 v46, 32, v183
	v_cmp_lt_i32_e32 vcc, v46, v48
	s_nop 1
	v_cndmask_b32_e32 v46, v183, v46, vcc
	v_lshlrev_b32_e32 v204, 2, v46
	ds_bpermute_b32 v46, v204, v13
	s_waitcnt lgkmcnt(0)
; __device__ __forceinline__ unsigned cvtpk(float lo, float hi) { const f32v2_t v = {lo, hi}; const bf16v2_t b = __builtin_convertvector(v, bf16v2_t); return __builtin_bit_cast(unsigned, b); }
; __device__ __forceinline__ v4i16_t lds_tr16(const bf16_t* p) { return __builtin_amdgcn_ds_read_tr16_b64_v4i16((LAS v4i16_t*)p); }
; __device__ void phase_attn(const Params& p, unsigned char* smem, int wave) {
;     ...
;         mx = fmaxf(mx, __shfl_xor(mx, 16)); mx = fmaxf(mx, __shfl_xor(mx, 32));
;         float den = 0.f;
; #pragma unroll
;         for (int kt = 0; kt < 9; ++kt)
; #pragma unroll
;             for (int j = 0; j < 4; ++j) { const float pv = __builtin_amdgcn_exp2f(sc[kt][j] - mx); sc[kt][j] = pv; den += pv; }
;         sc[9] = (f32x4){0.f, 0.f, 0.f, 0.f};
;         den += __shfl_xor(den, 16); den += __shfl_xor(den, 32);
;         f32x4 oacc[4];
; #pragma unroll
;         for (int et = 0; et < 4; ++et) oacc[et] = (f32x4){0.f, 0.f, 0.f, 0.f};
; #pragma unroll
;         for (int ks = 0; ks < 5; ++ks) {
;             u32x4 pu; pu.x = cvtpk(sc[2 * ks][0], sc[2 * ks][1]); pu.y = cvtpk(sc[2 * ks][2], sc[2 * ks][3]); pu.z = cvtpk(sc[2 * ks + 1][0], sc[2 * ks + 1][1]); pu.w = cvtpk(sc[2 * ks + 1][2], sc[2 * ks + 1][3]);
;             const bf16x8 pf = __builtin_bit_cast(bf16x8, pu);
;             const bf16_t* vrow = Vs + (16 * w4 + 32 * ks + 4 * gq + (ql >> 2)) * ATT_LD + 4 * (ql & 3);
; #pragma unroll
;             for (int et = 0; et < 4; ++et) {
;                 const v4i16_t t0 = lds_tr16(vrow + 16 * et);
;                 v4i16_t t1 = (v4i16_t){0, 0, 0, 0};
;                 if (ks < 4) t1 = lds_tr16(vrow + 16 * ATT_LD + 16 * et);
;                 const bf16x8 vf = __builtin_shufflevector(t0, t1, 0, 1, 2, 3, 4, 5, 6, 7);
;                 oacc[et] = __builtin_amdgcn_mfma_f32_16x16x32_bf16(pf, vf, oacc[et], 0, 0, 0); }
	v_max_f32_e32 v46, v46, v46
	v_max_f32_e32 v46, v13, v46
	v_sub_f32_e32 v13, v194, v46
	v_exp_f32_e32 v13, v13
	v_sub_f32_e32 v49, v195, v46
	v_exp_f32_e32 v49, v49
	v_sub_f32_e32 v194, v196, v46
	v_exp_f32_e32 v194, v194
	v_sub_f32_e32 v195, v197, v46
	v_exp_f32_e32 v195, v195
	v_sub_f32_e32 v14, v14, v46
	v_add_f32_e32 v48, 0, v13
	v_exp_f32_e32 v14, v14
	v_sub_f32_e32 v188, v188, v46
	v_add_f32_e32 v48, v49, v48
	v_exp_f32_e32 v188, v188
	v_sub_f32_e32 v189, v189, v46
	v_add_f32_e32 v48, v194, v48
	v_exp_f32_e32 v189, v189
	v_sub_f32_e32 v190, v190, v46
	v_add_f32_e32 v48, v195, v48
	v_exp_f32_e32 v190, v190
	v_sub_f32_e32 v191, v191, v46
	v_add_f32_e32 v48, v14, v48
	v_exp_f32_e32 v191, v191
	v_sub_f32_e32 v192, v192, v46
	v_add_f32_e32 v48, v188, v48
	v_exp_f32_e32 v192, v192
	v_sub_f32_e32 v193, v193, v46
	v_add_f32_e32 v48, v189, v48
	v_exp_f32_e32 v193, v193
	v_sub_f32_e32 v196, v198, v46
	v_add_f32_e32 v48, v190, v48
	v_exp_f32_e32 v196, v196
	v_sub_f32_e32 v197, v199, v46
	v_add_f32_e32 v48, v191, v48
	v_exp_f32_e32 v197, v197
	v_sub_f32_e32 v198, v200, v46
	v_add_f32_e32 v48, v192, v48
	v_exp_f32_e32 v198, v198
	v_sub_f32_e32 v199, v201, v46
	v_add_f32_e32 v48, v193, v48
	v_exp_f32_e32 v199, v199
	v_sub_f32_e32 v200, v202, v46
	v_add_f32_e32 v48, v196, v48
	v_exp_f32_e32 v200, v200
	v_sub_f32_e32 v186, v186, v46
	v_add_f32_e32 v48, v197, v48
	v_exp_f32_e32 v207, v186
	v_sub_f32_e32 v186, v187, v46
	v_add_f32_e32 v48, v198, v48
	v_exp_f32_e32 v208, v186
	v_sub_f32_e32 v64, v64, v46
	v_add_f32_e32 v48, v199, v48
	v_exp_f32_e32 v64, v64
	v_sub_f32_e32 v65, v65, v46
	v_add_f32_e32 v48, v200, v48
	v_exp_f32_e32 v65, v65
	v_sub_f32_e32 v62, v62, v46
	v_add_f32_e32 v48, v207, v48
	v_exp_f32_e32 v209, v62
	v_sub_f32_e32 v62, v63, v46
	v_add_f32_e32 v48, v208, v48
	v_exp_f32_e32 v210, v62
	v_sub_f32_e32 v60, v60, v46
	v_add_f32_e32 v48, v64, v48
	v_exp_f32_e32 v211, v60
	v_sub_f32_e32 v60, v61, v46
	v_add_f32_e32 v48, v65, v48
	v_exp_f32_e32 v212, v60
	v_sub_f32_e32 v58, v58, v46
	v_add_f32_e32 v48, v209, v48
	v_exp_f32_e32 v213, v58
	v_sub_f32_e32 v58, v59, v46
	v_add_f32_e32 v48, v210, v48
	v_exp_f32_e32 v214, v58
	v_sub_f32_e32 v56, v56, v46
	v_add_f32_e32 v48, v211, v48
	v_exp_f32_e32 v215, v56
	v_sub_f32_e32 v56, v57, v46
	v_add_f32_e32 v48, v212, v48
	v_exp_f32_e32 v216, v56
	v_sub_f32_e32 v54, v54, v46
	v_add_f32_e32 v48, v213, v48
	v_exp_f32_e32 v217, v54
	v_sub_f32_e32 v54, v55, v46
	v_add_f32_e32 v48, v214, v48
	v_exp_f32_e32 v218, v54
	v_sub_f32_e32 v52, v52, v46
	v_add_f32_e32 v48, v215, v48
	v_exp_f32_e32 v219, v52
	v_sub_f32_e32 v52, v53, v46
	v_add_f32_e32 v48, v216, v48
	v_exp_f32_e32 v220, v52
	v_sub_f32_e32 v50, v50, v46
	v_add_f32_e32 v48, v217, v48
	v_exp_f32_e32 v221, v50
	v_add_f32_e32 v48, v218, v48
	v_add_f32_e32 v48, v219, v48
	v_add_f32_e32 v48, v220, v48
	v_add_f32_e32 v201, v221, v48
	v_sub_f32_e32 v48, v51, v46
	v_exp_f32_e32 v222, v48
	v_sub_f32_e32 v47, v47, v46
	v_cvt_pk_bf16_f32 v48, v13, v49
	v_exp_f32_e32 v13, v47
	v_sub_f32_e32 v12, v12, v46
	v_cvt_pk_bf16_f32 v50, v14, v188
	v_exp_f32_e32 v14, v12
	v_add_f32_e32 v12, v222, v201
	v_add_f32_e32 v12, v13, v12
	v_cvt_pk_bf16_f32 v49, v194, v195
	v_add_f32_e32 v12, v14, v12
	ds_bpermute_b32 v47, v203, v12
	v_cvt_pk_bf16_f32 v51, v189, v190
	ds_read_b64_tr_b16 v[54:55], v179 offset:57600
	ds_read_b64_tr_b16 v[52:53], v179 offset:55296
	ds_read_b64_tr_b16 v[56:57], v179 offset:55328
	ds_read_b64_tr_b16 v[60:61], v179 offset:55360
	ds_read_b64_tr_b16 v[186:187], v179 offset:55392
	ds_read_b64_tr_b16 v[58:59], v179 offset:57632
	ds_read_b64_tr_b16 v[62:63], v179 offset:57664
	ds_read_b64_tr_b16 v[188:189], v179 offset:57696
	s_waitcnt lgkmcnt(6)
	v_mfma_f32_16x16x32_bf16 v[52:55], v[48:51], v[52:55], 0
	v_add_f32_e32 v47, v12, v47
	ds_bpermute_b32 v223, v204, v47
	s_waitcnt lgkmcnt(3)
	v_mfma_f32_16x16x32_bf16 v[56:59], v[48:51], v[56:59], 0
	s_waitcnt lgkmcnt(2)
	v_mfma_f32_16x16x32_bf16 v[60:63], v[48:51], v[60:63], 0
	s_waitcnt lgkmcnt(1)
	v_mfma_f32_16x16x32_bf16 v[48:51], v[48:51], v[186:189], 0
	v_cvt_pk_bf16_f32 v186, v191, v192
	v_cvt_pk_bf16_f32 v187, v193, v196
	v_cvt_pk_bf16_f32 v188, v197, v198
	v_cvt_pk_bf16_f32 v189, v199, v200
	ds_read_b64_tr_b16 v[192:193], v179 offset:62208
	ds_read_b64_tr_b16 v[190:191], v179 offset:59904
	ds_read_b64_tr_b16 v[194:195], v179 offset:59936
	ds_read_b64_tr_b16 v[198:199], v179 offset:59968
	ds_read_b64_tr_b16 v[202:203], v179 offset:60000
	ds_read_b64_tr_b16 v[196:197], v179 offset:62240
	ds_read_b64_tr_b16 v[200:201], v179 offset:62272
	ds_read_b64_tr_b16 v[204:205], v179 offset:62304
	s_waitcnt lgkmcnt(6)
	v_mfma_f32_16x16x32_bf16 v[52:55], v[186:189], v[190:193], v[52:55]
	s_waitcnt lgkmcnt(2)
	v_mfma_f32_16x16x32_bf16 v[56:59], v[186:189], v[194:197], v[56:59]
	s_waitcnt lgkmcnt(1)
	v_mfma_f32_16x16x32_bf16 v[60:63], v[186:189], v[198:201], v[60:63]
	s_waitcnt lgkmcnt(0)
	v_mfma_f32_16x16x32_bf16 v[48:51], v[186:189], v[202:205], v[48:51]
	v_cvt_pk_bf16_f32 v186, v207, v208
	v_cvt_pk_bf16_f32 v187, v64, v65
	v_cvt_pk_bf16_f32 v188, v209, v210
	v_cvt_pk_bf16_f32 v189, v211, v212
	ds_read_b64_tr_b16 v[192:193], v180 offset:11520
	ds_read_b64_tr_b16 v[190:191], v179 offset:64512
	ds_read_b64_tr_b16 v[194:195], v179 offset:64544
	ds_read_b64_tr_b16 v[198:199], v179 offset:64576
	ds_read_b64_tr_b16 v[202:203], v179 offset:64608
	ds_read_b64_tr_b16 v[196:197], v180 offset:11552
	ds_read_b64_tr_b16 v[200:201], v180 offset:11584
	ds_read_b64_tr_b16 v[204:205], v180 offset:11616
	s_waitcnt lgkmcnt(6)
	v_mfma_f32_16x16x32_bf16 v[52:55], v[186:189], v[190:193], v[52:55]
	s_waitcnt lgkmcnt(2)
; __device__ __forceinline__ unsigned cvtpk(float lo, float hi) { const f32v2_t v = {lo, hi}; const bf16v2_t b = __builtin_convertvector(v, bf16v2_t); return __builtin_bit_cast(unsigned, b); }
; __device__ __forceinline__ bf16_t f2bf(float f) { return (bf16_t)cvtpk(f, 0.f); }
; __device__ __forceinline__ v4i16_t lds_tr16(const bf16_t* p) { return __builtin_amdgcn_ds_read_tr16_b64_v4i16((LAS v4i16_t*)p); }
; __device__ void phase_attn(const Params& p, unsigned char* smem, int wave) {
;     ...
;         for (int ks = 0; ks < 5; ++ks) {
;             u32x4 pu; pu.x = cvtpk(sc[2 * ks][0], sc[2 * ks][1]); pu.y = cvtpk(sc[2 * ks][2], sc[2 * ks][3]); pu.z = cvtpk(sc[2 * ks + 1][0], sc[2 * ks + 1][1]); pu.w = cvtpk(sc[2 * ks + 1][2], sc[2 * ks + 1][3]);
;             const bf16x8 pf = __builtin_bit_cast(bf16x8, pu);
;             const bf16_t* vrow = Vs + (16 * w4 + 32 * ks + 4 * gq + (ql >> 2)) * ATT_LD + 4 * (ql & 3);
; #pragma unroll
;             for (int et = 0; et < 4; ++et) {
;                 const v4i16_t t0 = lds_tr16(vrow + 16 * et);
;                 v4i16_t t1 = (v4i16_t){0, 0, 0, 0};
;                 if (ks < 4) t1 = lds_tr16(vrow + 16 * ATT_LD + 16 * et);
;                 const bf16x8 vf = __builtin_shufflevector(t0, t1, 0, 1, 2, 3, 4, 5, 6, 7);
;                 oacc[et] = __builtin_amdgcn_mfma_f32_16x16x32_bf16(pf, vf, oacc[et], 0, 0, 0); }
;             __builtin_amdgcn_sched_barrier(0);
;         }
; #pragma unroll
;         for (int j = 0; j < 4; ++j) { const float dq = __shfl(den, 4 * gq + j); const float inv = __builtin_amdgcn_rcpf(dq);
;             const int tok = gbase + (i0 + 16 * w4 + 4 * gq + j) * d + res;
; #pragma unroll
;             for (int et = 0; et < 4; ++et) ato[(size_t)tok * 512 + h * 64 + 16 * et + ql] = f2bf(oacc[et][j] * inv); }
;         if (gq == 0) { const int tok = gbase + qi * d + res; lse[((size_t)br * NTOK + tok) * 8 + h] = mx * 0.6931471805599453f + __logf(den); }
	v_mfma_f32_16x16x32_bf16 v[56:59], v[186:189], v[194:197], v[56:59]
	s_waitcnt lgkmcnt(1)
	v_mfma_f32_16x16x32_bf16 v[60:63], v[186:189], v[198:201], v[60:63]
	s_waitcnt lgkmcnt(0)
	v_mfma_f32_16x16x32_bf16 v[48:51], v[186:189], v[202:205], v[48:51]
	v_cvt_pk_bf16_f32 v186, v213, v214
	v_cvt_pk_bf16_f32 v187, v215, v216
	v_cvt_pk_bf16_f32 v188, v217, v218
	v_cvt_pk_bf16_f32 v189, v219, v220
	ds_read_b64_tr_b16 v[192:193], v180 offset:16128
	ds_read_b64_tr_b16 v[190:191], v180 offset:13824
	ds_read_b64_tr_b16 v[194:195], v180 offset:13856
	ds_read_b64_tr_b16 v[198:199], v180 offset:13888
	ds_read_b64_tr_b16 v[202:203], v180 offset:13920
	ds_read_b64_tr_b16 v[196:197], v180 offset:16160
	ds_read_b64_tr_b16 v[200:201], v180 offset:16192
	ds_read_b64_tr_b16 v[204:205], v180 offset:16224
	s_waitcnt lgkmcnt(6)
	v_mfma_f32_16x16x32_bf16 v[52:55], v[186:189], v[190:193], v[52:55]
	s_waitcnt lgkmcnt(2)
	v_mfma_f32_16x16x32_bf16 v[56:59], v[186:189], v[194:197], v[56:59]
	s_waitcnt lgkmcnt(1)
	v_mfma_f32_16x16x32_bf16 v[60:63], v[186:189], v[198:201], v[60:63]
	s_waitcnt lgkmcnt(0)
	v_mfma_f32_16x16x32_bf16 v[48:51], v[186:189], v[202:205], v[48:51]
	v_cvt_pk_bf16_f32 v12, v221, v222
	v_cvt_pk_bf16_f32 v13, v13, v14
	v_mov_b32_e32 v14, v15
	ds_read_b64_tr_b16 v[186:187], v180 offset:18432
	ds_read_b64_tr_b16 v[190:191], v180 offset:18464
	ds_read_b64_tr_b16 v[194:195], v180 offset:18496
	ds_read_b64_tr_b16 v[198:199], v180 offset:18528
	v_mov_b32_e32 v188, v15
	v_mov_b32_e32 v189, v15
	v_mov_b32_e32 v192, v15
	v_mov_b32_e32 v193, v15
	v_mov_b32_e32 v196, v15
	v_mov_b32_e32 v197, v15
	v_mov_b32_e32 v200, v15
	v_mov_b32_e32 v201, v15
	s_waitcnt lgkmcnt(3)
	v_mfma_f32_16x16x32_bf16 v[52:55], v[12:15], v[186:189], v[52:55]
	s_waitcnt lgkmcnt(2)
	v_mfma_f32_16x16x32_bf16 v[56:59], v[12:15], v[190:193], v[56:59]
	s_waitcnt lgkmcnt(1)
	v_mfma_f32_16x16x32_bf16 v[60:63], v[12:15], v[194:197], v[60:63]
	s_waitcnt lgkmcnt(0)
	v_mfma_f32_16x16x32_bf16 v[48:51], v[12:15], v[198:201], v[48:51]
	v_or_b32_e32 v14, v206, v141
	v_add_f32_e32 v12, v47, v223
	v_lshlrev_b32_e32 v14, 2, v14
	ds_bpermute_b32 v47, v14, v12
	s_add_i32 s62, s62, s61
	s_lshl_b32 s18, s57, 7
	s_add_u32 s18, s59, s18
	v_or_b32_e32 v13, v139, v141
	s_addc_u32 s19, s60, 0
	v_mov_b32_e32 v139, v15
	s_waitcnt lgkmcnt(0)
	v_rcp_f32_e32 v47, v47
	v_lshl_add_u64 v[64:65], s[18:19], 0, v[138:139]
	v_lshlrev_b32_e32 v139, s58, v13
	v_add_u32_e32 v186, s62, v139
	v_ashrrev_i32_e32 v187, 31, v186
	v_lshlrev_b64 v[186:187], 10, v[186:187]
	v_mul_f32_e32 v52, v52, v47
	v_lshl_add_u64 v[186:187], v[64:65], 0, v[186:187]
	v_cvt_pk_bf16_f32 v52, v52, s0
	global_store_short v[186:187], v52, off
	v_mul_f32_e32 v52, v56, v47
	ds_bpermute_b32 v56, v14, v12 offset:4
	v_cvt_pk_bf16_f32 v52, v52, s0
	global_store_short v[186:187], v52, off offset:32
	v_mul_f32_e32 v52, v60, v47
	v_mul_f32_e32 v47, v48, v47
	v_cvt_pk_bf16_f32 v47, v47, s0
	global_store_short v[186:187], v47, off offset:96
	s_waitcnt lgkmcnt(0)
	v_rcp_f32_e32 v47, v56
	v_or_b32_e32 v48, 1, v13
	v_cvt_pk_bf16_f32 v52, v52, s0
	v_lshlrev_b32_e32 v48, s58, v48
	global_store_short v[186:187], v52, off offset:64
	v_add_u32_e32 v186, s62, v48
	v_ashrrev_i32_e32 v187, 31, v186
	v_lshlrev_b64 v[186:187], 10, v[186:187]
	v_mul_f32_e32 v48, v53, v47
	v_lshl_add_u64 v[186:187], v[64:65], 0, v[186:187]
	v_cvt_pk_bf16_f32 v48, v48, s0
	ds_bpermute_b32 v52, v14, v12 offset:8
	global_store_short v[186:187], v48, off
	v_mul_f32_e32 v48, v57, v47
	v_cvt_pk_bf16_f32 v48, v48, s0
	global_store_short v[186:187], v48, off offset:32
	v_mul_f32_e32 v48, v61, v47
	v_mul_f32_e32 v47, v49, v47
	v_cvt_pk_bf16_f32 v48, v48, s0
	v_cvt_pk_bf16_f32 v47, v47, s0
	global_store_short v[186:187], v48, off offset:64
	global_store_short v[186:187], v47, off offset:96
	s_waitcnt lgkmcnt(0)
	v_rcp_f32_e32 v47, v52
	v_or_b32_e32 v48, 2, v13
	v_lshlrev_b32_e32 v48, s58, v48
	v_add_u32_e32 v48, s62, v48
	v_or_b32_e32 v14, 12, v14
	v_ashrrev_i32_e32 v49, 31, v48
	ds_bpermute_b32 v14, v14, v12
	v_lshlrev_b64 v[48:49], 10, v[48:49]
	v_mul_f32_e32 v52, v54, v47
	v_lshl_add_u64 v[48:49], v[64:65], 0, v[48:49]
	v_cvt_pk_bf16_f32 v52, v52, s0
	global_store_short v[48:49], v52, off
	v_mul_f32_e32 v52, v58, v47
	v_cvt_pk_bf16_f32 v52, v52, s0
	global_store_short v[48:49], v52, off offset:32
	v_mul_f32_e32 v52, v62, v47
	v_mul_f32_e32 v47, v50, v47
	s_waitcnt lgkmcnt(0)
	v_rcp_f32_e32 v14, v14
	v_or_b32_e32 v13, 3, v13
	v_cvt_pk_bf16_f32 v52, v52, s0
	v_cvt_pk_bf16_f32 v47, v47, s0
	v_lshlrev_b32_e32 v13, s58, v13
	global_store_short v[48:49], v52, off offset:64
	global_store_short v[48:49], v47, off offset:96
	v_add_u32_e32 v48, s62, v13
	v_ashrrev_i32_e32 v49, 31, v48
	v_lshlrev_b64 v[48:49], 10, v[48:49]
	v_mul_f32_e32 v13, v55, v14
	v_lshl_add_u64 v[48:49], v[64:65], 0, v[48:49]
	v_cvt_pk_bf16_f32 v13, v13, s0
	global_store_short v[48:49], v13, off
	v_mul_f32_e32 v13, v59, v14
	v_cvt_pk_bf16_f32 v13, v13, s0
	global_store_short v[48:49], v13, off offset:32
	v_mul_f32_e32 v13, v63, v14
	v_cvt_pk_bf16_f32 v13, v13, s0
	global_store_short v[48:49], v13, off offset:64
	v_mul_f32_e32 v13, v51, v14
	v_cvt_pk_bf16_f32 v13, v13, s0
	global_store_short v[48:49], v13, off offset:96
	s_and_saveexec_b64 s[20:21], s[0:1]
	s_cbranch_execz .LBB0_719
	v_cmp_gt_f32_e32 vcc, s53, v12
	s_nop 1
	v_cndmask_b32_e64 v13, 0, 32, vcc
	v_ldexp_f32 v12, v12, v13
	v_log_f32_e32 v13, v12
	v_lshlrev_b32_e32 v12, s58, v45
	v_add_u32_e32 v12, s62, v12
	v_mul_f32_e32 v14, 0x3f317217, v13
	v_fma_f32 v14, v13, s54, -v14
	v_fmac_f32_e32 v14, 0x3377d1cf, v13
	v_fmac_f32_e32 v14, 0x3f317217, v13
	v_cmp_lt_f32_e64 s[18:19], |v13|, s55
	s_nop 1
	v_cndmask_b32_e64 v13, v13, v14, s[18:19]
	v_cndmask_b32_e32 v14, 0, v184, vcc
	v_sub_f32_e32 v14, v13, v14
	v_ashrrev_i32_e32 v13, 31, v12
	v_mad_i64_i32 v[12:13], s[18:19], s42, v185, v[12:13]
	v_lshlrev_b64 v[12:13], 5, v[12:13]
	v_lshl_add_u64 v[12:13], s[40:41], 0, v[12:13]
	s_lshl_b32 s42, s57, 2
	v_fmac_f32_e32 v14, 0x3f317218, v46
	v_lshl_add_u64 v[12:13], v[12:13], 0, s[42:43]
	global_store_dword v[12:13], v14, off
	s_branch .LBB0_719
